# stage A publishes G[ch]=exp(last prefix sum); stage C forms exp(cl-cm) as G*exp(-cm) and exp(cm) as 1/exp(-cm): 24 instead of 40 transcendental ops per thread
# speedup vs baseline: 1.0464x; 1.0066x over previous
.LBB0_931:
	s_andn2_b64 vcc, exec, s[10:11]
	s_movk_i32 s10, 0x2080
	s_cbranch_vccnz .LBB0_933
	v_mul_f32_e32 v41, 0xbfb8aa3b, v95
	v_exp_f32_e32 v41, v41
	v_mul_f32_e32 v42, 0xbfb8aa3b, v94
	v_mul_f32_e32 v43, 0xbfb8aa3b, v93
	v_exp_f32_e32 v44, v42
	v_exp_f32_e32 v43, v43
	v_add_f32_e32 v41, 1.0, v41
	v_rcp_f32_e32 v42, v41
	v_add_f32_e32 v41, 1.0, v44
	v_rcp_f32_e32 v44, v41
	v_add_f32_e32 v41, 1.0, v43
	v_mul_f32_e32 v43, 0xbfb8aa3b, v92
	v_mul_f32_e32 v38, 0xbfb8aa3b, v38
	v_exp_f32_e32 v45, v43
	v_mul_f32_e32 v43, 0xbfb8aa3b, v91
	v_exp_f32_e32 v38, v38
	v_exp_f32_e32 v46, v43
	v_rcp_f32_e32 v43, v41
	v_add_f32_e32 v41, 1.0, v45
	v_add_f32_e32 v38, 1.0, v38
	v_mul_f32_e32 v37, 0xbfb8aa3b, v37
	v_rcp_f32_e32 v45, v41
	v_add_f32_e32 v41, 1.0, v46
	v_mul_f32_e32 v46, 0xbfb8aa3b, v90
	v_rcp_f32_e32 v100, v38
	v_exp_f32_e32 v38, v37
	v_exp_f32_e32 v47, v46
	v_mul_f32_e32 v40, 0xbfb8aa3b, v40
	v_mul_f32_e32 v36, 0xbfb8aa3b, v36
	v_mul_f32_e32 v46, 0xbfb8aa3b, v89
	v_exp_f32_e32 v40, v40
	v_add_f32_e32 v38, 1.0, v38
	v_exp_f32_e32 v36, v36
	v_mul_f32_e32 v35, 0xbfb8aa3b, v35
	v_mul_f32_e32 v33, 0xbfb8aa3b, v33
	v_exp_f32_e32 v89, v46
	v_rcp_f32_e32 v46, v41
	v_add_f32_e32 v41, 1.0, v47
	v_mul_f32_e32 v47, 0xbfb8aa3b, v88
	v_rcp_f32_e32 v116, v38
	v_exp_f32_e32 v38, v35
	v_mul_f32_e32 v34, 0xbfb8aa3b, v34
	v_exp_f32_e32 v33, v33
	v_exp_f32_e32 v88, v47
	v_exp_f32_e32 v34, v34
	v_add_f32_e32 v40, 1.0, v40
	v_add_f32_e32 v36, 1.0, v36
	v_rcp_f32_e32 v90, v41
	v_add_f32_e32 v41, 1.0, v89
	v_rcp_f32_e32 v98, v40
	v_rcp_f32_e32 v40, v36
	v_add_f32_e32 v36, 1.0, v38
	v_add_f32_e32 v33, 1.0, v33
	v_cmp_lt_i32_e32 vcc, v108, v109
	v_pk_mul_f32 v[44:45], v[44:45], s[34:35] op_sel_hi:[1,0]
	v_rcp_f32_e32 v47, v41
	v_add_f32_e32 v41, 1.0, v88
	v_rcp_f32_e32 v88, v36
	v_add_f32_e32 v34, 1.0, v34
	v_rcp_f32_e32 v89, v33
	v_cndmask_b32_e32 v33, v107, v108, vcc
	v_pk_mul_f32 v[92:93], v[42:43], s[34:35] op_sel_hi:[1,0]
	v_pk_fma_f32 v[42:43], v[42:43], s[34:35], v[44:45] op_sel_hi:[1,0,1]
	v_rcp_f32_e32 v91, v41
	v_rcp_f32_e32 v41, v34
	v_lshlrev_b32_e32 v33, 2, v33
	v_add_f32_e32 v34, v42, v43
	v_mul_f32_e32 v39, 0xbfb8aa3b, v39
	ds_bpermute_b32 v38, v33, v34
	v_exp_f32_e32 v39, v39
	v_pk_mul_f32 v[88:89], v[88:89], s[34:35] op_sel_hi:[1,0]
	v_pk_mul_f32 v[90:91], v[90:91], s[34:35] op_sel_hi:[1,0]
	v_pk_mul_f32 v[94:95], v[40:41], s[34:35] op_sel_hi:[1,0]
	v_pk_fma_f32 v[40:41], v[40:41], s[34:35], v[88:89] op_sel_hi:[1,0,1]
	v_pk_mul_f32 v[42:43], v[46:47], s[34:35] op_sel_hi:[1,0]
	v_pk_fma_f32 v[46:47], v[46:47], s[34:35], v[90:91] op_sel_hi:[1,0,1]
	v_pk_add_f32 v[40:41], v[40:41], v[40:41] op_sel:[0,1] op_sel_hi:[1,0]
	v_add_f32_e32 v39, 1.0, v39
	v_pk_add_f32 v[46:47], v[46:47], v[46:47] op_sel:[0,1] op_sel_hi:[1,0]
	s_waitcnt lgkmcnt(0)
	v_add_f32_e32 v41, 0, v38
	v_cmp_eq_u32_e32 vcc, 0, v115
	v_rcp_f32_e32 v99, v39
	ds_bpermute_b32 v36, v33, v46
	v_cndmask_b32_e64 v41, v41, 0, vcc
	v_add_f32_e32 v41, v92, v41
	v_lshl_add_u32 v92, v114, 2, v32
	v_add_f32_e32 v44, v44, v41
	v_mul_f32_e32 v101, 0xbf1b459e, v98
	ds_write2_b32 v92, v41, v44 offset1:65
	v_add_f32_e32 v41, v93, v44
	v_mul_f32_e32 v37, 0xbf1b459e, v99
	v_mul_f32_e32 v39, 0xbf1b459e, v100
	v_mul_f32_e32 v35, 0xbf1b459e, v116
	v_add_f32_e32 v44, v45, v41
	v_add_f32_e32 v38, v34, v38
	v_mov_b32_e32 v34, v97
	v_mov_b32_e32 v47, v101
	ds_write2_b32 v92, v41, v44 offset0:130 offset1:195
	s_waitcnt lgkmcnt(2)
	v_cndmask_b32_e64 v41, v36, 0, vcc
	v_pk_add_f32 v[34:35], v[38:39], v[34:35]
	v_pk_add_f32 v[36:37], v[46:47], v[36:37]
	ds_bpermute_b32 v40, v33, v40
	v_pk_add_f32 v[36:37], v[36:37], v[34:35]
	ds_bpermute_b32 v33, v33, v37
	v_add_f32_e32 v34, v34, v41
	v_add_f32_e32 v34, v42, v34
	v_add_f32_e32 v35, v90, v34
	v_add_u32_e32 v38, 0x800, v92
	ds_write2_b32 v38, v34, v35 offset0:8 offset1:73
	v_add_f32_e32 v34, v43, v35
	v_add_f32_e32 v35, v91, v34
	ds_write2_b32 v38, v34, v35 offset0:138 offset1:203
	s_waitcnt lgkmcnt(2)
	v_cndmask_b32_e64 v34, v33, 0, vcc
	v_add_f32_e32 v34, v36, v34
	v_fmac_f32_e32 v34, 0xbf1b459e, v98
	v_fmamk_f32 v35, v99, 0xbf1b459e, v34
	v_add_u32_e32 v38, 0x1000, v92
	ds_write2_b32 v38, v34, v35 offset0:16 offset1:81
	v_fmac_f32_e32 v35, 0xbf1b459e, v100
	v_fmamk_f32 v34, v116, 0xbf1b459e, v35
	v_add_f32_e32 v33, v37, v33
	ds_write2_b32 v38, v35, v34 offset0:146 offset1:211
	v_add_f32_e32 v33, v36, v33
	v_cndmask_b32_e64 v34, v40, 0, vcc
	v_add_f32_e32 v33, v33, v34
	v_add_f32_e32 v33, v94, v33
	v_add_f32_e32 v34, v88, v33
	v_add_u32_e32 v35, 0x1800, v92
	ds_write2_b32 v35, v33, v34 offset0:24 offset1:89
	v_add_f32_e32 v33, v95, v34
	s_mov_b32 s10, 0
	v_add_f32_e32 v43, v89, v33
	v_mul_f32_e32 v213, 0x3fb8aa3b, v43
	v_lshlrev_b32_e32 v214, 8, v115
	v_exp_f32_e32 v213, v213
	v_lshlrev_b32_e32 v215, 2, v114
	v_sub_u32_e32 v214, v215, v214
	v_add_u32_e32 v214, 0x11380, v214
	ds_write_b32 v214, v213
	v_mov_b32_e32 v42, v32
	ds_write_b32 v92, v33 offset:6760
.LBB0_933:
	v_lshlrev_b32_e32 v32, 2, v114
	v_add3_u32 v32, s10, v32, v42
	v_and_b32_e32 v116, 7, v113
	ds_write_b32 v32, v43 offset:7020
	s_waitcnt lgkmcnt(0)
	s_barrier
	s_setprio 1
	s_waitcnt vmcnt(0)
	v_lshrrev_b32_e32 v41, 3, v113
	v_lshlrev_b32_e32 v168, 5, v116
	v_mul_u32_u24_e32 v136, 0x104, v41
	v_cmp_lt_u32_e32 vcc, 0, v41
	v_add_u32_e32 v169, v136, v168
	v_mov_b32_e32 v137, 0x104
	v_add_u32_e32 v170, 0x2080, v169
	ds_read_b128 v[178:181], v168 offset:61120
	ds_read_b128 v[182:185], v168 offset:61136
	ds_read2_b32 v[194:195], v170 offset0:0 offset1:1
	ds_read2_b32 v[196:197], v170 offset0:2 offset1:3
	ds_read2_b32 v[198:199], v170 offset0:4 offset1:5
	ds_read2_b32 v[200:201], v170 offset0:6 offset1:7
	ds_read_b128 v[208:211], v168 offset:61376
	ds_read_b128 v[212:215], v168 offset:61392
	ds_read2_b32 v[224:225], v169 offset0:0 offset1:1
	ds_read2_b32 v[226:227], v169 offset0:2 offset1:3
	ds_read2_b32 v[228:229], v169 offset0:4 offset1:5
	ds_read2_b32 v[230:231], v169 offset0:6 offset1:7
	v_mov_b32_e32 v232, 0x3fb8aa3b
	v_mov_b32_e32 v233, 0x3fb8aa3b
	v_cndmask_b32_e32 v137, 0, v137, vcc
	v_cndmask_b32_e32 v171, 0, v232, vcc
	v_mov_b32_e32 v234, 1.0
	v_mov_b32_e32 v235, 1.0
	v_sub_u32_e32 v172, v169, v137
	v_add_u32_e32 v173, 0x11280, v168
	v_mul_u32_u24_e32 v174, 0x280, v116
	v_lshrrev_b32_e32 v136, 3, v41
	v_and_b32_e32 v138, 4, v116
	v_xor_b32_e32 v136, v136, v116
	v_lshl_add_u32 v174, v138, 4, v174
	v_and_b32_e32 v136, 3, v136
	v_and_b32_e32 v138, 7, v41
	v_lshl_add_u32 v174, v136, 4, v174
	v_mul_u32_u24_e32 v175, 0x90, v41
	v_lshl_add_u32 v174, v138, 1, v174
	v_lshl_add_u32 v175, v116, 4, v175
	v_lshlrev_b32_e32 v186, 16, v84
	v_and_b32_e32 v187, 0xffff0000, v84
	v_lshlrev_b32_e32 v188, 16, v85
	v_and_b32_e32 v189, 0xffff0000, v85
	v_lshlrev_b32_e32 v190, 16, v86
	v_and_b32_e32 v191, 0xffff0000, v86
	v_lshlrev_b32_e32 v192, 16, v87
	v_and_b32_e32 v193, 0xffff0000, v87
	s_waitcnt lgkmcnt(0)
	ds_read_b128 v[120:123], v173 offset:0
	ds_read_b128 v[124:127], v173 offset:16
	ds_read2_b32 v[128:129], v172 offset0:0 offset1:1
	ds_read2_b32 v[130:131], v172 offset0:2 offset1:3
	ds_read2_b32 v[132:133], v172 offset0:4 offset1:5
	ds_read2_b32 v[134:135], v172 offset0:6 offset1:7
	v_pk_mul_f32 v[178:179], v[178:179], v[186:187]
	v_pk_mul_f32 v[180:181], v[180:181], v[188:189]
	v_pk_mul_f32 v[182:183], v[182:183], v[190:191]
	v_pk_mul_f32 v[184:185], v[184:185], v[192:193]
	v_pk_mul_f32 v[166:167], v[178:179], v[178:179]
	v_pk_fma_f32 v[166:167], v[180:181], v[180:181], v[166:167]
	v_pk_fma_f32 v[166:167], v[182:183], v[182:183], v[166:167]
	v_pk_fma_f32 v[166:167], v[184:185], v[184:185], v[166:167]
	v_pk_add_f32 v[216:217], v[194:195], v[234:235] neg_lo:[0,1] neg_hi:[0,1]
	v_pk_add_f32 v[218:219], v[196:197], v[234:235] neg_lo:[0,1] neg_hi:[0,1]
	v_pk_add_f32 v[220:221], v[198:199], v[234:235] neg_lo:[0,1] neg_hi:[0,1]
	v_pk_add_f32 v[222:223], v[200:201], v[234:235] neg_lo:[0,1] neg_hi:[0,1]
	v_add_f32_e32 v166, v166, v167
	v_pk_fma_f32 v[208:209], v[216:217], v[208:209], v[234:235]
	v_pk_fma_f32 v[210:211], v[218:219], v[210:211], v[234:235]
	v_add_f32_dpp v166, v166, v166 quad_perm:[1,0,3,2] row_mask:0xf bank_mask:0xf bound_ctrl:1
	v_pk_fma_f32 v[212:213], v[220:221], v[212:213], v[234:235]
	v_pk_fma_f32 v[214:215], v[222:223], v[214:215], v[234:235]
	v_add_f32_dpp v166, v166, v166 quad_perm:[2,3,0,1] row_mask:0xf bank_mask:0xf bound_ctrl:1
	v_pk_mul_f32 v[186:187], v[186:187], v[208:209]
	v_pk_mul_f32 v[188:189], v[188:189], v[210:211]
	v_mov_b32_dpp v167, v166 row_half_mirror row_mask:0xf bank_mask:0xf bound_ctrl:1
	v_pk_mul_f32 v[190:191], v[190:191], v[212:213]
	v_pk_mul_f32 v[192:193], v[192:193], v[214:215]
	v_add_f32_e32 v166, v166, v167
	v_add_f32_e32 v166, 0x2b8cbccc, v166
	v_rsq_f32_e32 v166, v166
	s_waitcnt lgkmcnt(0)
	v_pk_mul_f32 v[178:179], v[178:179], v[166:167] op_sel_hi:[1,0]
	v_pk_mul_f32 v[180:181], v[180:181], v[166:167] op_sel_hi:[1,0]
	v_pk_mul_f32 v[182:183], v[182:183], v[166:167] op_sel_hi:[1,0]
	v_pk_mul_f32 v[184:185], v[184:185], v[166:167] op_sel_hi:[1,0]
	v_cmp_eq_u32_e32 vcc, 31, v41
	v_pk_mul_f32 v[216:217], v[178:179], v[194:195]
	v_pk_mul_f32 v[218:219], v[180:181], v[196:197]
	v_pk_mul_f32 v[220:221], v[182:183], v[198:199]
	v_pk_mul_f32 v[222:223], v[184:185], v[200:201]
	s_and_saveexec_b64 s[38:39], vcc
	s_cbranch_execz .Lc_nogc_a
	ds_write_b128 v168, v[120:123] offset:60864
	ds_write_b128 v168, v[124:127] offset:60880
.Lc_nogc_a:
	s_or_b64 exec, exec, s[38:39]
	v_pk_mul_f32 v[224:225], v[224:225], v[232:233]
	v_pk_mul_f32 v[226:227], v[226:227], v[232:233]
	v_pk_mul_f32 v[228:229], v[228:229], v[232:233]
	v_pk_mul_f32 v[230:231], v[230:231], v[232:233]
	v_mul_f32_e32 v128, v171, v128
	v_mul_f32_e32 v129, v171, v129
	v_mul_f32_e32 v130, v171, v130
	v_mul_f32_e32 v131, v171, v131
	v_mul_f32_e32 v132, v171, v132
	v_mul_f32_e32 v133, v171, v133
	v_mul_f32_e32 v134, v171, v134
	v_mul_f32_e32 v135, v171, v135
	v_exp_f32_e64 v194, -v224
	v_exp_f32_e64 v195, -v225
	v_exp_f32_e64 v196, -v226
	v_exp_f32_e64 v197, -v227
	v_exp_f32_e64 v198, -v228
	v_exp_f32_e64 v199, -v229
	v_exp_f32_e64 v200, -v230
	v_exp_f32_e64 v201, -v231
	v_exp_f32_e64 v128, v128
	v_exp_f32_e64 v129, v129
	v_exp_f32_e64 v130, v130
	v_exp_f32_e64 v131, v131
	v_exp_f32_e64 v132, v132
	v_exp_f32_e64 v133, v133
	v_exp_f32_e64 v134, v134
	v_exp_f32_e64 v135, v135
	v_pk_mul_f32 v[120:121], v[120:121], v[194:195]
	v_pk_mul_f32 v[122:123], v[122:123], v[196:197]
	v_pk_mul_f32 v[124:125], v[124:125], v[198:199]
	v_pk_mul_f32 v[126:127], v[126:127], v[200:201]
	v_pk_mul_f32 v[224:225], v[216:217], v[120:121]
	v_pk_mul_f32 v[226:227], v[218:219], v[122:123]
	v_pk_mul_f32 v[228:229], v[220:221], v[124:125]
	v_pk_mul_f32 v[230:231], v[222:223], v[126:127]
	v_pk_mul_f32 v[120:121], v[186:187], v[120:121]
	v_pk_mul_f32 v[122:123], v[188:189], v[122:123]
	v_pk_mul_f32 v[124:125], v[190:191], v[124:125]
	v_pk_mul_f32 v[126:127], v[192:193], v[126:127]
	v_cvt_pk_bf16_f32 v224, v224, v225
	v_cvt_pk_bf16_f32 v225, v226, v227
	v_cvt_pk_bf16_f32 v226, v228, v229
	v_cvt_pk_bf16_f32 v227, v230, v231
	v_cvt_pk_bf16_f32 v228, v120, v121
	v_cvt_pk_bf16_f32 v229, v122, v123
	v_cvt_pk_bf16_f32 v230, v124, v125
	v_cvt_pk_bf16_f32 v231, v126, v127
	ds_write_b16 v174, v224 offset:35072
	ds_write_b16_d16_hi v174, v224 offset:35152
	ds_write_b16 v174, v225 offset:35232
	ds_write_b16_d16_hi v174, v225 offset:35312
	ds_write_b16 v174, v226 offset:35392
	ds_write_b16_d16_hi v174, v226 offset:35472
	ds_write_b16 v174, v227 offset:35552
	ds_write_b16_d16_hi v174, v227 offset:35632
	ds_write_b16 v174, v228 offset:40256
	ds_write_b16_d16_hi v174, v228 offset:40336
	ds_write_b16 v174, v229 offset:40416
	s_waitcnt lgkmcnt(5)
	ds_write_b16_d16_hi v174, v229 offset:40496
	ds_write_b16 v174, v230 offset:40576
	ds_write_b16_d16_hi v174, v230 offset:40656
	ds_write_b16 v174, v231 offset:40736
	ds_write_b16_d16_hi v174, v231 offset:40816
	ds_write_b16 v174, v80 offset:45440
	ds_write_b16_d16_hi v174, v80 offset:45520
	ds_write_b16 v174, v81 offset:45600
	s_waitcnt lgkmcnt(5)
	ds_write_b16_d16_hi v174, v81 offset:45680
	ds_write_b16 v174, v82 offset:45760
	ds_write_b16_d16_hi v174, v82 offset:45840
	ds_write_b16 v174, v83 offset:45920
	ds_write_b16_d16_hi v174, v83 offset:46000
	v_pk_mul_f32 v[128:129], v[178:179], v[128:129] neg_lo:[1,0] neg_hi:[1,0]
	v_pk_mul_f32 v[130:131], v[180:181], v[130:131] neg_lo:[1,0] neg_hi:[1,0]
	v_pk_mul_f32 v[132:133], v[182:183], v[132:133] neg_lo:[1,0] neg_hi:[1,0]
	v_pk_mul_f32 v[134:135], v[184:185], v[134:135] neg_lo:[1,0] neg_hi:[1,0]
	v_cvt_pk_bf16_f32 v128, v128, v129
	v_cvt_pk_bf16_f32 v129, v130, v131
	v_cvt_pk_bf16_f32 v130, v132, v133
	v_cvt_pk_bf16_f32 v131, v134, v135
	s_waitcnt lgkmcnt(8)
	ds_write_b128 v175, v[128:131] offset:16640
	v_pk_mul_f32 v[216:217], v[216:217], v[194:195]
	v_pk_mul_f32 v[218:219], v[218:219], v[196:197]
	v_pk_mul_f32 v[220:221], v[220:221], v[198:199]
	v_pk_mul_f32 v[222:223], v[222:223], v[200:201]
	v_pk_mul_f32 v[186:187], v[186:187], v[194:195]
	v_pk_mul_f32 v[188:189], v[188:189], v[196:197]
	v_pk_mul_f32 v[190:191], v[190:191], v[198:199]
	v_pk_mul_f32 v[192:193], v[192:193], v[200:201]
	v_cvt_pk_bf16_f32 v216, v216, v217
	v_cvt_pk_bf16_f32 v217, v218, v219
	v_cvt_pk_bf16_f32 v218, v220, v221
	v_cvt_pk_bf16_f32 v219, v222, v223
	v_cvt_pk_bf16_f32 v186, v186, v187
	v_cvt_pk_bf16_f32 v187, v188, v189
	v_cvt_pk_bf16_f32 v188, v190, v191
	v_cvt_pk_bf16_f32 v189, v192, v193
	s_waitcnt lgkmcnt(8)
	ds_write_b128 v175, v[216:219] offset:25856
	ds_write_b128 v175, v[186:189] offset:30464
	v_lshlrev_b32_e32 v47, 3, v116
	s_andn2_b64 vcc, exec, s[36:37]
	s_cbranch_vccnz .LBB0_967
	v_sub_u32_e32 v32, 31, v41
	v_cndmask_b32_e64 v32, v32, v41, s[6:7]
	v_add_u32_e32 v32, s54, v32
	v_ashrrev_i32_e32 v33, 31, v32
	v_or_b32_e32 v36, s35, v47
	v_lshlrev_b64 v[32:33], 11, v[32:33]
	v_lshl_add_u64 v[34:35], s[16:17], 0, v[32:33]
	v_lshlrev_b32_e32 v36, 1, v36
	v_mov_b32_e32 v37, v97
	v_lshl_add_u64 v[34:35], v[34:35], 0, v[36:37]
	v_lshl_add_u64 v[32:33], s[26:27], 0, v[32:33]
	v_lshl_add_u64 v[32:33], v[32:33], 0, v[36:37]
	global_load_dwordx4 v[84:87], v[34:35], off
	global_load_dwordx4 v[80:83], v[32:33], off

.LBB0_1109:
	s_mov_b64 s[12:13], -1
	s_andn2_b64 vcc, exec, s[8:9]
	s_nop 7
	v_add_f32_e32 v58, v157, v34
	v_mul_u32_u24_e32 v34, 0x410, v51
	v_add_f32_e32 v57, v157, v35
	v_add_f32_e32 v56, v157, v36
	v_add_f32_e32 v55, v157, v37
	v_add_f32_e32 v54, v157, v38
	v_add_f32_e32 v53, v157, v39
	v_add_f32_e32 v52, v157, v40
	v_add_f32_e32 v50, v157, v41
	v_add_f32_e32 v42, v157, v42
	v_add_f32_e32 v41, v157, v43
	v_add_f32_e32 v40, v157, v44
	v_add_f32_e32 v39, v157, v45
	v_add_f32_e32 v38, v157, v46
	v_add_f32_e32 v37, v157, v47
	v_add_f32_e32 v36, v157, v48
	v_add_f32_e32 v35, v157, v49
	s_cbranch_vccnz .LBB0_1111
	v_mul_f32_e32 v43, 0xbfb8aa3b, v58
	v_mul_f32_e32 v45, 0xbfb8aa3b, v57
	v_exp_f32_e32 v44, v43
	v_exp_f32_e32 v45, v45
	v_mul_f32_e32 v48, 0xbfb8aa3b, v56
	v_mul_f32_e32 v49, 0xbfb8aa3b, v55
	v_add_f32_e32 v44, 1.0, v44
	v_add_f32_e32 v45, 1.0, v45
	v_rcp_f32_e32 v44, v44
	v_rcp_f32_e32 v45, v45
	v_exp_f32_e32 v48, v48
	v_exp_f32_e32 v49, v49
	v_mul_u32_u24_e32 v43, 0x410, v51
	v_lshl_add_u32 v46, v71, 2, v43
	v_add_u32_e32 v46, 0xd180, v46
	v_add_u32_e32 v47, 0x2000, v46
	ds_write2_b32 v47, v44, v45 offset0:32 offset1:97
	v_add_f32_e32 v44, 1.0, v48
	v_add_f32_e32 v45, 1.0, v49
	v_mul_f32_e32 v48, 0xbfb8aa3b, v54
	v_mul_f32_e32 v49, 0xbfb8aa3b, v53
	v_rcp_f32_e32 v44, v44
	v_rcp_f32_e32 v45, v45
	v_exp_f32_e32 v48, v48
	v_exp_f32_e32 v49, v49
	s_mov_b64 s[12:13], 0
	ds_write2_b32 v47, v44, v45 offset0:162 offset1:227
	v_add_f32_e32 v44, 1.0, v48
	v_add_f32_e32 v45, 1.0, v49
	v_mul_f32_e32 v48, 0xbfb8aa3b, v52
	v_mul_f32_e32 v49, 0xbfb8aa3b, v50
	v_rcp_f32_e32 v44, v44
	v_rcp_f32_e32 v45, v45
	v_exp_f32_e32 v48, v48
	v_exp_f32_e32 v49, v49
	v_add_u32_e32 v47, 0x2800, v46
	ds_write2_b32 v47, v44, v45 offset0:40 offset1:105
	v_add_f32_e32 v44, 1.0, v48
	v_add_f32_e32 v45, 1.0, v49
	v_mul_f32_e32 v48, 0xbfb8aa3b, v42
	v_mul_f32_e32 v49, 0xbfb8aa3b, v41
	v_rcp_f32_e32 v44, v44
	v_rcp_f32_e32 v45, v45
	v_exp_f32_e32 v48, v48
	v_exp_f32_e32 v49, v49
	ds_write2_b32 v47, v44, v45 offset0:170 offset1:235
	v_add_f32_e32 v44, 1.0, v48
	v_add_f32_e32 v45, 1.0, v49
	v_mul_f32_e32 v48, 0xbfb8aa3b, v40
	v_mul_f32_e32 v49, 0xbfb8aa3b, v39
	v_rcp_f32_e32 v44, v44
	v_rcp_f32_e32 v45, v45
	v_exp_f32_e32 v48, v48
	v_exp_f32_e32 v49, v49
	v_add_u32_e32 v47, 0x3000, v46
	ds_write2_b32 v47, v44, v45 offset0:48 offset1:113
	v_add_f32_e32 v44, 1.0, v48
	v_add_f32_e32 v45, 1.0, v49
	v_mul_f32_e32 v48, 0xbfb8aa3b, v38
	v_rcp_f32_e32 v44, v44
	v_rcp_f32_e32 v45, v45
	v_exp_f32_e32 v48, v48
	v_mul_f32_e32 v49, 0xbfb8aa3b, v37
	v_exp_f32_e32 v49, v49
	ds_write2_b32 v47, v44, v45 offset0:178 offset1:243
	v_add_f32_e32 v44, 1.0, v48
	v_rcp_f32_e32 v45, v44
	v_add_f32_e32 v44, 1.0, v49
	v_rcp_f32_e32 v47, v44
	v_mul_f32_e32 v44, 0xbfb8aa3b, v36
	v_exp_f32_e32 v44, v44
	v_mul_f32_e32 v48, 0xbfb8aa3b, v35
	v_exp_f32_e32 v48, v48
	v_add_u32_e32 v49, 0x3800, v46
	v_add_f32_e32 v44, 1.0, v44
	v_rcp_f32_e32 v59, v44
	v_add_f32_e32 v44, 1.0, v48
	v_rcp_f32_e32 v44, v44
	ds_write2_b32 v49, v45, v47 offset0:56 offset1:121
	ds_write_b32 v46, v59 offset:15080
	.LBB0_1111:
	s_andn2_b64 vcc, exec, s[12:13]
	s_mov_b32 s12, 0xf200
	s_cbranch_vccnz .LBB0_1113
	s_setprio 1
	v_mul_f32_e32 v43, 0xbfb8aa3b, v58
	v_exp_f32_e32 v43, v43
	v_mul_f32_e32 v44, 0xbfb8aa3b, v57
	v_mul_f32_e32 v45, 0xbfb8aa3b, v56
	v_exp_f32_e32 v46, v44
	v_exp_f32_e32 v45, v45
	v_add_f32_e32 v43, 1.0, v43
	v_rcp_f32_e32 v44, v43
	v_add_f32_e32 v43, 1.0, v46
	v_rcp_f32_e32 v46, v43
	v_add_f32_e32 v43, 1.0, v45
	v_mul_f32_e32 v45, 0xbfb8aa3b, v55
	v_exp_f32_e32 v47, v45
	v_mul_f32_e32 v45, 0xbfb8aa3b, v54
	v_mul_f32_e32 v40, 0xbfb8aa3b, v40
	v_exp_f32_e32 v48, v45
	v_exp_f32_e32 v40, v40
	v_rcp_f32_e32 v45, v43
	v_add_f32_e32 v43, 1.0, v47
	v_rcp_f32_e32 v47, v43
	v_add_f32_e32 v43, 1.0, v48
	v_mul_f32_e32 v48, 0xbfb8aa3b, v53
	v_add_f32_e32 v40, 1.0, v40
	v_mul_f32_e32 v39, 0xbfb8aa3b, v39
	v_exp_f32_e32 v49, v48
	v_rcp_f32_e32 v61, v40
	v_exp_f32_e32 v40, v39
	v_mul_f32_e32 v48, 0xbfb8aa3b, v52
	v_mul_f32_e32 v42, 0xbfb8aa3b, v42
	v_mul_f32_e32 v38, 0xbfb8aa3b, v38
	v_exp_f32_e32 v53, v48
	v_rcp_f32_e32 v48, v43
	v_add_f32_e32 v43, 1.0, v49
	v_mul_f32_e32 v49, 0xbfb8aa3b, v50
	v_exp_f32_e32 v42, v42
	v_add_f32_e32 v40, 1.0, v40
	v_exp_f32_e32 v38, v38
	v_mul_f32_e32 v37, 0xbfb8aa3b, v37
	v_mul_f32_e32 v35, 0xbfb8aa3b, v35
	v_exp_f32_e32 v50, v49
	v_rcp_f32_e32 v63, v40
	v_exp_f32_e32 v40, v37
	v_mul_f32_e32 v36, 0xbfb8aa3b, v36
	v_exp_f32_e32 v35, v35
	v_exp_f32_e32 v36, v36
	v_rcp_f32_e32 v52, v43
	v_add_f32_e32 v43, 1.0, v53
	v_add_f32_e32 v42, 1.0, v42
	v_add_f32_e32 v38, 1.0, v38
	v_rcp_f32_e32 v49, v43
	v_add_f32_e32 v43, 1.0, v50
	v_rcp_f32_e32 v50, v42
	v_rcp_f32_e32 v42, v38
	v_add_f32_e32 v38, 1.0, v40
	v_add_f32_e32 v35, 1.0, v35
	v_cmp_lt_i32_e32 vcc, v153, v154
	v_pk_mul_f32 v[46:47], v[46:47], s[42:43] op_sel_hi:[1,0]
	v_rcp_f32_e32 v54, v38
	v_add_f32_e32 v36, 1.0, v36
	v_rcp_f32_e32 v55, v35
	v_cndmask_b32_e32 v35, v152, v153, vcc
	v_pk_mul_f32 v[56:57], v[44:45], s[42:43] op_sel_hi:[1,0]
	v_pk_fma_f32 v[44:45], v[44:45], s[42:43], v[46:47] op_sel_hi:[1,0,1]
	v_rcp_f32_e32 v53, v43
	v_rcp_f32_e32 v43, v36
	v_lshlrev_b32_e32 v35, 2, v35
	v_add_f32_e32 v36, v44, v45
	v_mul_f32_e32 v41, 0xbfb8aa3b, v41
	ds_bpermute_b32 v40, v35, v36
	v_exp_f32_e32 v41, v41
	v_pk_mul_f32 v[54:55], v[54:55], s[42:43] op_sel_hi:[1,0]
	v_pk_mul_f32 v[52:53], v[52:53], s[42:43] op_sel_hi:[1,0]
	v_pk_mul_f32 v[58:59], v[42:43], s[42:43] op_sel_hi:[1,0]
	v_pk_fma_f32 v[42:43], v[42:43], s[42:43], v[54:55] op_sel_hi:[1,0,1]
	v_pk_mul_f32 v[44:45], v[48:49], s[42:43] op_sel_hi:[1,0]
	v_pk_fma_f32 v[48:49], v[48:49], s[42:43], v[52:53] op_sel_hi:[1,0,1]
	v_pk_add_f32 v[42:43], v[42:43], v[42:43] op_sel:[0,1] op_sel_hi:[1,0]
	v_add_f32_e32 v41, 1.0, v41
	v_pk_add_f32 v[48:49], v[48:49], v[48:49] op_sel:[0,1] op_sel_hi:[1,0]
	s_waitcnt lgkmcnt(0)
	v_add_f32_e32 v43, 0, v40
	v_cmp_eq_u32_e32 vcc, 0, v51
	v_rcp_f32_e32 v60, v41
	ds_bpermute_b32 v38, v35, v48
	v_cndmask_b32_e64 v43, v43, 0, vcc
	v_add_f32_e32 v43, v56, v43
	v_lshl_add_u32 v56, v71, 2, v34
	v_add_f32_e32 v46, v46, v43
	v_mul_f32_e32 v62, 0xbf1b459e, v50
	ds_write2_b32 v56, v43, v46 offset1:65
	v_add_f32_e32 v43, v57, v46
	v_mul_f32_e32 v39, 0xbf1b459e, v60
	v_mul_f32_e32 v41, 0xbf1b459e, v61
	v_mul_f32_e32 v37, 0xbf1b459e, v63
	v_add_f32_e32 v46, v47, v43
	v_add_f32_e32 v40, v36, v40
	v_mov_b32_e32 v36, v1
	v_mov_b32_e32 v49, v62
	ds_write2_b32 v56, v43, v46 offset0:130 offset1:195
	s_waitcnt lgkmcnt(2)
	v_cndmask_b32_e64 v43, v38, 0, vcc
	v_pk_add_f32 v[36:37], v[40:41], v[36:37]
	v_pk_add_f32 v[38:39], v[48:49], v[38:39]
	ds_bpermute_b32 v42, v35, v42
	v_pk_add_f32 v[38:39], v[38:39], v[36:37]
	ds_bpermute_b32 v35, v35, v39
	v_add_f32_e32 v36, v36, v43
	v_add_f32_e32 v36, v44, v36
	v_add_f32_e32 v37, v52, v36
	v_add_u32_e32 v40, 0x800, v56
	ds_write2_b32 v40, v36, v37 offset0:8 offset1:73
	v_add_f32_e32 v36, v45, v37
	v_add_f32_e32 v37, v53, v36
	ds_write2_b32 v40, v36, v37 offset0:138 offset1:203
	s_waitcnt lgkmcnt(2)
	v_cndmask_b32_e64 v36, v35, 0, vcc
	v_add_f32_e32 v36, v38, v36
	v_fmac_f32_e32 v36, 0xbf1b459e, v50
	v_fmamk_f32 v37, v60, 0xbf1b459e, v36
	v_add_u32_e32 v40, 0x1000, v56
	ds_write2_b32 v40, v36, v37 offset0:16 offset1:81
	v_fmac_f32_e32 v37, 0xbf1b459e, v61
	v_fmamk_f32 v36, v63, 0xbf1b459e, v37
	v_add_f32_e32 v35, v39, v35
	ds_write2_b32 v40, v37, v36 offset0:146 offset1:211
	v_add_f32_e32 v35, v38, v35
	v_cndmask_b32_e64 v36, v42, 0, vcc
	v_add_f32_e32 v35, v35, v36
	v_add_f32_e32 v35, v58, v35
	v_add_f32_e32 v36, v54, v35
	v_add_u32_e32 v37, 0x1800, v56
	ds_write2_b32 v37, v35, v36 offset0:24 offset1:89
	v_add_f32_e32 v35, v59, v36
	s_mov_b32 s12, 0
	v_add_f32_e32 v44, v55, v35
	v_mul_f32_e32 v213, 0x3fb8aa3b, v44
	v_lshlrev_b32_e32 v214, 8, v51
	v_exp_f32_e32 v213, v213
	v_lshlrev_b32_e32 v215, 2, v71
	v_sub_u32_e32 v214, v215, v214
	v_add_u32_e32 v214, 0x11380, v214
	ds_write_b32 v214, v213
	v_mov_b32_e32 v43, v34
	ds_write_b32 v56, v35 offset:6760
	.LBB0_1113:
	s_setprio 0
	v_lshlrev_b32_e32 v144, 2, v71
	v_add3_u32 v34, s12, v144, v43
	v_and_b32_e32 v73, 7, v141
	ds_write_b32 v34, v44 offset:7020
	s_branch .La_join_b

.La_join_b:
	s_waitcnt lgkmcnt(0)
	s_barrier
	s_setprio 1
	s_waitcnt vmcnt(0)
	v_lshrrev_b32_e32 v72, 3, v141
	v_lshlrev_b32_e32 v50, 5, v73
	v_mul_u32_u24_e32 v161, 0x104, v72
	v_cmp_lt_u32_e32 vcc, 0, v72
	v_add_u32_e32 v68, v161, v50
	v_mov_b32_e32 v162, 0x104
	v_add_u32_e32 v69, 0xf200, v68
	ds_read_b128 v[214:217], v50 offset:61120
	ds_read_b128 v[218:221], v50 offset:61136
	ds_read2_b32 v[34:35], v69 offset0:0 offset1:1
	ds_read2_b32 v[36:37], v69 offset0:2 offset1:3
	ds_read2_b32 v[38:39], v69 offset0:4 offset1:5
	ds_read2_b32 v[40:41], v69 offset0:6 offset1:7
	ds_read_b128 v[42:45], v50 offset:61376
	ds_read_b128 v[46:49], v50 offset:61392
	ds_read2_b32 v[60:61], v68 offset0:0 offset1:1
	ds_read2_b32 v[62:63], v68 offset0:2 offset1:3
	ds_read2_b32 v[64:65], v68 offset0:4 offset1:5
	ds_read2_b32 v[66:67], v68 offset0:6 offset1:7
	v_mov_b32_e32 v230, 0x3fb8aa3b
	v_mov_b32_e32 v231, 0x3fb8aa3b
	v_cndmask_b32_e32 v162, 0, v162, vcc
	v_cndmask_b32_e32 v143, 0, v230, vcc
	v_mov_b32_e32 v232, 1.0
	v_mov_b32_e32 v233, 1.0
	v_sub_u32_e32 v145, v68, v162
	v_add_u32_e32 v158, 0x11280, v50
	v_mul_u32_u24_e32 v159, 0x280, v73
	v_lshrrev_b32_e32 v161, 3, v72
	v_and_b32_e32 v163, 4, v73
	v_xor_b32_e32 v161, v161, v73
	v_lshl_add_u32 v159, v163, 4, v159
	v_and_b32_e32 v161, 3, v161
	v_and_b32_e32 v163, 7, v72
	v_lshl_add_u32 v159, v161, 4, v159
	v_mul_u32_u24_e32 v160, 0x90, v72
	v_lshl_add_u32 v159, v163, 1, v159
	v_lshl_add_u32 v160, v73, 4, v160
	v_lshlrev_b32_e32 v222, 16, v122
	v_and_b32_e32 v223, 0xffff0000, v122
	v_lshlrev_b32_e32 v224, 16, v123
	v_and_b32_e32 v225, 0xffff0000, v123
	v_lshlrev_b32_e32 v226, 16, v124
	v_and_b32_e32 v227, 0xffff0000, v124
	v_lshlrev_b32_e32 v228, 16, v125
	v_and_b32_e32 v229, 0xffff0000, v125
	s_waitcnt lgkmcnt(0)
	ds_read_b128 v[74:77], v158 offset:0
	ds_read_b128 v[78:81], v158 offset:16
	ds_read2_b32 v[126:127], v145 offset0:0 offset1:1
	ds_read2_b32 v[128:129], v145 offset0:2 offset1:3
	ds_read2_b32 v[130:131], v145 offset0:4 offset1:5
	ds_read2_b32 v[132:133], v145 offset0:6 offset1:7
	v_pk_mul_f32 v[214:215], v[214:215], v[222:223]
	v_pk_mul_f32 v[216:217], v[216:217], v[224:225]
	v_pk_mul_f32 v[218:219], v[218:219], v[226:227]
	v_pk_mul_f32 v[220:221], v[220:221], v[228:229]
	v_pk_mul_f32 v[234:235], v[214:215], v[214:215]
	v_pk_fma_f32 v[234:235], v[216:217], v[216:217], v[234:235]
	v_pk_fma_f32 v[234:235], v[218:219], v[218:219], v[234:235]
	v_pk_fma_f32 v[234:235], v[220:221], v[220:221], v[234:235]
	v_pk_add_f32 v[52:53], v[34:35], v[232:233] neg_lo:[0,1] neg_hi:[0,1]
	v_pk_add_f32 v[54:55], v[36:37], v[232:233] neg_lo:[0,1] neg_hi:[0,1]
	v_pk_add_f32 v[56:57], v[38:39], v[232:233] neg_lo:[0,1] neg_hi:[0,1]
	v_pk_add_f32 v[58:59], v[40:41], v[232:233] neg_lo:[0,1] neg_hi:[0,1]
	v_add_f32_e32 v234, v234, v235
	v_pk_fma_f32 v[42:43], v[52:53], v[42:43], v[232:233]
	v_pk_fma_f32 v[44:45], v[54:55], v[44:45], v[232:233]
	v_add_f32_dpp v234, v234, v234 quad_perm:[1,0,3,2] row_mask:0xf bank_mask:0xf bound_ctrl:1
	v_pk_fma_f32 v[46:47], v[56:57], v[46:47], v[232:233]
	v_pk_fma_f32 v[48:49], v[58:59], v[48:49], v[232:233]
	v_add_f32_dpp v234, v234, v234 quad_perm:[2,3,0,1] row_mask:0xf bank_mask:0xf bound_ctrl:1
	v_pk_mul_f32 v[222:223], v[222:223], v[42:43]
	v_pk_mul_f32 v[224:225], v[224:225], v[44:45]
	v_mov_b32_dpp v235, v234 row_half_mirror row_mask:0xf bank_mask:0xf bound_ctrl:1
	v_pk_mul_f32 v[226:227], v[226:227], v[46:47]
	v_pk_mul_f32 v[228:229], v[228:229], v[48:49]
	ds_read_b128 v[42:45], v50 offset:61632
	ds_read_b128 v[46:49], v50 offset:61648
	v_add_f32_e32 v234, v234, v235
	v_add_f32_e32 v234, 0x2b8cbccc, v234
	v_rsq_f32_e32 v234, v234
	s_waitcnt lgkmcnt(2)
	v_pk_mul_f32 v[214:215], v[214:215], v[234:235] op_sel_hi:[1,0]
	v_pk_mul_f32 v[216:217], v[216:217], v[234:235] op_sel_hi:[1,0]
	v_pk_mul_f32 v[218:219], v[218:219], v[234:235] op_sel_hi:[1,0]
	v_pk_mul_f32 v[220:221], v[220:221], v[234:235] op_sel_hi:[1,0]
	v_cmp_eq_u32_e32 vcc, 31, v72
	v_pk_mul_f32 v[52:53], v[214:215], v[34:35]
	v_pk_mul_f32 v[54:55], v[216:217], v[36:37]
	v_pk_mul_f32 v[56:57], v[218:219], v[38:39]
	v_pk_mul_f32 v[58:59], v[220:221], v[40:41]
	s_and_saveexec_b64 s[60:61], vcc
	s_cbranch_execz .Lc_nogc_b
	ds_write_b128 v50, v[74:77] offset:60864
	ds_write_b128 v50, v[78:81] offset:60880
.Lc_nogc_b:
	s_or_b64 exec, exec, s[60:61]
	v_pk_mul_f32 v[60:61], v[60:61], v[230:231]
	v_pk_mul_f32 v[62:63], v[62:63], v[230:231]
	v_pk_mul_f32 v[64:65], v[64:65], v[230:231]
	v_pk_mul_f32 v[66:67], v[66:67], v[230:231]
	v_mul_f32_e32 v126, v143, v126
	v_mul_f32_e32 v127, v143, v127
	v_mul_f32_e32 v128, v143, v128
	v_mul_f32_e32 v129, v143, v129
	v_mul_f32_e32 v130, v143, v130
	v_mul_f32_e32 v131, v143, v131
	v_mul_f32_e32 v132, v143, v132
	v_mul_f32_e32 v133, v143, v133
	v_exp_f32_e64 v34, -v60
	v_exp_f32_e64 v35, -v61
	v_exp_f32_e64 v36, -v62
	v_exp_f32_e64 v37, -v63
	v_exp_f32_e64 v38, -v64
	v_exp_f32_e64 v39, -v65
	v_exp_f32_e64 v40, -v66
	v_exp_f32_e64 v41, -v67
	v_exp_f32_e64 v126, v126
	v_exp_f32_e64 v127, v127
	v_exp_f32_e64 v128, v128
	v_exp_f32_e64 v129, v129
	v_exp_f32_e64 v130, v130
	v_exp_f32_e64 v131, v131
	v_exp_f32_e64 v132, v132
	v_exp_f32_e64 v133, v133
	v_pk_mul_f32 v[74:75], v[74:75], v[34:35]
	v_pk_mul_f32 v[76:77], v[76:77], v[36:37]
	v_pk_mul_f32 v[78:79], v[78:79], v[38:39]
	v_pk_mul_f32 v[80:81], v[80:81], v[40:41]
	v_pk_mul_f32 v[60:61], v[52:53], v[74:75]
	v_pk_mul_f32 v[62:63], v[54:55], v[76:77]
	v_pk_mul_f32 v[64:65], v[56:57], v[78:79]
	v_pk_mul_f32 v[66:67], v[58:59], v[80:81]
	v_pk_mul_f32 v[74:75], v[222:223], v[74:75]
	v_pk_mul_f32 v[76:77], v[224:225], v[76:77]
	v_pk_mul_f32 v[78:79], v[226:227], v[78:79]
	v_pk_mul_f32 v[80:81], v[228:229], v[80:81]
	v_cvt_pk_bf16_f32 v60, v60, v61
	v_cvt_pk_bf16_f32 v61, v62, v63
	v_cvt_pk_bf16_f32 v62, v64, v65
	v_cvt_pk_bf16_f32 v63, v66, v67
	v_cvt_pk_bf16_f32 v64, v74, v75
	v_cvt_pk_bf16_f32 v65, v76, v77
	v_cvt_pk_bf16_f32 v66, v78, v79
	v_cvt_pk_bf16_f32 v67, v80, v81
	ds_write_b16 v159, v60 offset:35072
	ds_write_b16_d16_hi v159, v60 offset:35152
	ds_write_b16 v159, v61 offset:35232
	ds_write_b16_d16_hi v159, v61 offset:35312
	ds_write_b16 v159, v62 offset:35392
	ds_write_b16_d16_hi v159, v62 offset:35472
	ds_write_b16 v159, v63 offset:35552
	ds_write_b16_d16_hi v159, v63 offset:35632
	ds_write_b16 v159, v64 offset:40256
	s_waitcnt lgkmcnt(5)
	ds_write_b16_d16_hi v159, v64 offset:40336
	ds_write_b16 v159, v65 offset:40416
	ds_write_b16_d16_hi v159, v65 offset:40496
	ds_write_b16 v159, v66 offset:40576
	ds_write_b16_d16_hi v159, v66 offset:40656
	ds_write_b16 v159, v67 offset:40736
	ds_write_b16_d16_hi v159, v67 offset:40816
	ds_write_b16 v159, v118 offset:45440
	s_waitcnt lgkmcnt(5)
	ds_write_b16_d16_hi v159, v118 offset:45520
	ds_write_b16 v159, v119 offset:45600
	ds_write_b16_d16_hi v159, v119 offset:45680
	ds_write_b16 v159, v120 offset:45760
	ds_write_b16_d16_hi v159, v120 offset:45840
	ds_write_b16 v159, v121 offset:45920
	ds_write_b16_d16_hi v159, v121 offset:46000
	v_pk_mul_f32 v[126:127], v[214:215], v[126:127] neg_lo:[1,0] neg_hi:[1,0]
	v_pk_mul_f32 v[128:129], v[216:217], v[128:129] neg_lo:[1,0] neg_hi:[1,0]
	v_pk_mul_f32 v[130:131], v[218:219], v[130:131] neg_lo:[1,0] neg_hi:[1,0]
	v_pk_mul_f32 v[132:133], v[220:221], v[132:133] neg_lo:[1,0] neg_hi:[1,0]
	v_cvt_pk_bf16_f32 v126, v126, v127
	v_cvt_pk_bf16_f32 v127, v128, v129
	v_cvt_pk_bf16_f32 v128, v130, v131
	v_cvt_pk_bf16_f32 v129, v132, v133
	s_waitcnt lgkmcnt(8)
	ds_write_b128 v160, v[126:129] offset:16640
	v_rcp_f32_e32 v74, v34
	v_rcp_f32_e32 v75, v35
	v_rcp_f32_e32 v76, v36
	v_rcp_f32_e32 v77, v37
	v_rcp_f32_e32 v78, v38
	v_rcp_f32_e32 v79, v39
	v_rcp_f32_e32 v80, v40
	v_rcp_f32_e32 v81, v41
	v_lshlrev_b32_e32 v126, 16, v114
	v_and_b32_e32 v127, 0xffff0000, v114
	v_lshlrev_b32_e32 v128, 16, v115
	v_and_b32_e32 v129, 0xffff0000, v115
	v_lshlrev_b32_e32 v130, 16, v116
	v_and_b32_e32 v131, 0xffff0000, v116
	v_lshlrev_b32_e32 v132, 16, v117
	v_and_b32_e32 v133, 0xffff0000, v117
	v_pk_mul_f32 v[42:43], v[42:43], v[126:127]
	v_pk_mul_f32 v[44:45], v[44:45], v[128:129]
	v_pk_mul_f32 v[46:47], v[46:47], v[130:131]
	v_pk_mul_f32 v[48:49], v[48:49], v[132:133]
	v_pk_mul_f32 v[126:127], v[126:127], v[74:75]
	v_pk_mul_f32 v[128:129], v[128:129], v[76:77]
	v_pk_mul_f32 v[130:131], v[130:131], v[78:79]
	v_pk_mul_f32 v[132:133], v[132:133], v[80:81]
	v_pk_mul_f32 v[234:235], v[42:43], v[222:223]
	v_pk_fma_f32 v[234:235], v[44:45], v[224:225], v[234:235]
	v_pk_fma_f32 v[234:235], v[46:47], v[226:227], v[234:235]
	v_pk_fma_f32 v[234:235], v[48:49], v[228:229], v[234:235]
	v_cvt_pk_bf16_f32 v126, v126, v127
	v_cvt_pk_bf16_f32 v127, v128, v129
	v_cvt_pk_bf16_f32 v128, v130, v131
	v_cvt_pk_bf16_f32 v129, v132, v133
	s_waitcnt lgkmcnt(8)
	ds_write_b128 v160, v[126:129] offset:21248
	v_pk_mul_f32 v[52:53], v[52:53], v[34:35]
	v_pk_mul_f32 v[54:55], v[54:55], v[36:37]
	v_pk_mul_f32 v[56:57], v[56:57], v[38:39]
	v_pk_mul_f32 v[58:59], v[58:59], v[40:41]
	v_pk_mul_f32 v[222:223], v[222:223], v[34:35]
	v_pk_mul_f32 v[224:225], v[224:225], v[36:37]
	v_pk_mul_f32 v[226:227], v[226:227], v[38:39]
	v_pk_mul_f32 v[228:229], v[228:229], v[40:41]
	v_cvt_pk_bf16_f32 v52, v52, v53
	v_cvt_pk_bf16_f32 v53, v54, v55
	v_cvt_pk_bf16_f32 v54, v56, v57
	v_cvt_pk_bf16_f32 v55, v58, v59
	v_cvt_pk_bf16_f32 v222, v222, v223
	v_cvt_pk_bf16_f32 v223, v224, v225
	v_cvt_pk_bf16_f32 v224, v226, v227
	v_cvt_pk_bf16_f32 v225, v228, v229
	s_waitcnt lgkmcnt(8)
	ds_write_b128 v160, v[52:55] offset:25856
	ds_write_b128 v160, v[222:225] offset:30464
	v_lshlrev_b32_e32 v57, 3, v73
	v_add_f32_e32 v38, v234, v235
	s_nop 1
	v_add_f32_dpp v34, v38, v38 quad_perm:[1,0,3,2] row_mask:0xf bank_mask:0xf bound_ctrl:1
	v_cmp_eq_u32_e32 vcc, 0, v73
	s_nop 0
	v_add_f32_dpp v34, v34, v34 quad_perm:[2,3,0,1] row_mask:0xf bank_mask:0xf bound_ctrl:1
	s_nop 1
	v_mov_b32_dpp v35, v34 row_half_mirror row_mask:0xf bank_mask:0xf bound_ctrl:1
	s_and_saveexec_b64 s[12:13], vcc
	s_cbranch_execz .LBB0_1147
	v_add_f32_e32 v34, v34, v35
	v_ashrrev_i32_e32 v143, 31, v142
	v_mul_f32_e32 v36, 0.5, v34
	v_lshlrev_b64 v[34:35], 6, v[142:143]
	v_lshl_add_u64 v[34:35], s[52:53], 0, v[34:35]
	global_atomic_add_f32 v[34:35], v36, off
